# scan rewrite + xcd barrier instead of cg grid sync at phase 0 + hand-written post1 (16B accesses, prefetch)
# speedup vs baseline: 1.0044x; 1.0044x over previous
; DI int ltid() { int t = __builtin_amdgcn_workitem_id_x(); asm volatile("" : "+v"(t)); return t; }
; DI void post1_rows(const Params& p, int l, int nrows, int bid, int nb) {
;   const int lane = ltid() & 63, wid = ltid() >> 6;
;   const int nw = nb * 4;
;   const u16* __restrict__ Z = (const u16*)(p.ws + OFF_ZRW);
;   const u16* __restrict__ YF = (const u16*)(p.ws + OFF_QK);
;   const u16* __restrict__ YB = YF + (size_t)NT * 512;
;   const float* __restrict__ BF = (const float*)(p.ws + OFF_BONUS);
;   const float* __restrict__ BB = BF + (size_t)NT * 8;
;   u16* __restrict__ U = (u16*)(p.ws + OFF_V);
;   u16* __restrict__ SG = U + (size_t)NT * 512;
;   const float* __restrict__ mu = p.rwkv_mu + l * RWB;
;   const float* __restrict__ ng = p.rwkv_norm_g + l * 512;
;   for (int row = bid * 4 + wid; row < nrows; row += nw) {
;     const int nrow = shift_nbr(row, lane);
; DI void run_phase(const Params& p, int ph, int bid, int nb, char* smem) {
;     ...
;   switch (s) {
;     case 0:
;       norm_rows(p, l, 0, NT, bid, nb);
;       if (l > 0) for (int it = bid; it < WC_TOTAL; it += nb) wconv_item(p, l, it, smem);
;       break;
;     case 1: gemm_in_phase<4>(p, l, bid, nb, smem); break;
;     case 2: for (int it = bid; it < 512; it += nb) retention_item(p, l, ctx_out, it, smem); break;
;     case 3: for (int it = bid; it < 256; it += nb) scan_item(p, l, ctx_out, it, smem); break;
;     case 4: post1_rows(p, l, mrows, bid, nb); break;
.LBB0_148:
	s_andn2_b64 vcc, exec, s[0:1]
	s_cbranch_vccnz .LBB0_814
	s_and_b32 s0, 0xffff, s71
	v_writelane_b32 v243, s0, 23
	s_cmp_lt_i32 s0, 2
	s_mov_b64 s[0:1], -1
	s_cbranch_scc1 .LBB0_496
	v_readlane_b32 s0, v243, 23
	v_readlane_b32 s36, v243, 19
	s_cmp_lt_i32 s0, 3
	s_mov_b64 s[0:1], -1
	v_readlane_b32 s37, v243, 20
	s_cbranch_scc1 .LBB0_464
	v_readlane_b32 s0, v243, 23
	s_cmp_gt_i32 s0, 3
	s_mov_b64 s[0:1], -1
	s_cbranch_scc0 .LBB0_196
	v_writelane_b32 v255, s0, 0
	v_writelane_b32 v255, s1, 1
	v_writelane_b32 v255, s2, 2
	v_writelane_b32 v255, s3, 3
	v_writelane_b32 v255, s4, 4
	v_writelane_b32 v255, s5, 5
	v_writelane_b32 v255, s6, 6
	v_writelane_b32 v255, s7, 7
	v_writelane_b32 v255, s8, 8
	v_writelane_b32 v255, s9, 9
	v_writelane_b32 v255, s10, 10
	v_writelane_b32 v255, s11, 11
	v_writelane_b32 v255, s12, 12
	v_writelane_b32 v255, s13, 13
	v_writelane_b32 v255, s14, 14
	v_writelane_b32 v255, s15, 15
	v_writelane_b32 v255, s16, 16
	v_writelane_b32 v255, s17, 17
	v_writelane_b32 v255, s18, 18
	v_writelane_b32 v255, s19, 19
	v_writelane_b32 v255, s20, 20
	v_writelane_b32 v255, s21, 21
	v_writelane_b32 v255, s22, 22
	v_writelane_b32 v255, s23, 23
	v_writelane_b32 v255, s24, 24
	v_writelane_b32 v255, s25, 25
	v_writelane_b32 v255, s26, 26
	v_writelane_b32 v255, s27, 27
	v_writelane_b32 v255, s28, 28
	v_writelane_b32 v255, s29, 29
	v_writelane_b32 v255, s30, 30
	v_writelane_b32 v255, s31, 31
	v_writelane_b32 v255, s32, 32
	v_writelane_b32 v255, s33, 33
	v_writelane_b32 v255, s34, 34
	v_writelane_b32 v255, s35, 35
	v_writelane_b32 v255, s36, 36
	v_writelane_b32 v255, s37, 37
	v_writelane_b32 v255, s38, 38
	v_writelane_b32 v255, s39, 39
	v_writelane_b32 v255, s40, 40
	v_writelane_b32 v255, s41, 41
	v_writelane_b32 v255, s42, 42
	v_writelane_b32 v255, s43, 43
	v_writelane_b32 v255, s44, 44
	v_writelane_b32 v255, s45, 45
	v_writelane_b32 v255, s46, 46
	v_writelane_b32 v255, s47, 47
	v_writelane_b32 v255, s48, 48
	v_writelane_b32 v255, s49, 49
	v_writelane_b32 v255, s50, 50
	v_writelane_b32 v255, s51, 51
	v_writelane_b32 v255, s52, 52
	v_writelane_b32 v255, s53, 53
	v_writelane_b32 v255, s54, 54
	v_writelane_b32 v255, s55, 55
	v_writelane_b32 v255, s56, 56
	v_writelane_b32 v255, s57, 57
	v_writelane_b32 v255, s58, 58
	v_writelane_b32 v255, s59, 59
	v_writelane_b32 v255, s60, 60
	v_writelane_b32 v255, s61, 61
	v_writelane_b32 v255, s62, 62
	v_writelane_b32 v255, s63, 63
	v_writelane_b32 v254, s64, 0
	v_writelane_b32 v254, s65, 1
	v_writelane_b32 v254, s66, 2
	v_writelane_b32 v254, s67, 3
	v_writelane_b32 v254, s68, 4
	v_writelane_b32 v254, s69, 5
	v_writelane_b32 v254, s70, 6
	v_writelane_b32 v254, s71, 7
	v_writelane_b32 v254, s72, 8
	v_writelane_b32 v254, s73, 9
	v_writelane_b32 v254, s74, 10
	v_writelane_b32 v254, s75, 11
	v_writelane_b32 v254, s76, 12
	v_writelane_b32 v254, s77, 13
	v_readlane_b32 s4, v246, 4
	v_readlane_b32 s5, v246, 5
	v_readlane_b32 s12, v244, 54
	v_readlane_b32 s13, v243, 8
	v_readlane_b32 s15, v243, 7
	s_sub_u32 s4, s4, 0xe8
	s_subb_u32 s5, s5, 0
	s_load_dwordx2 s[6:7], s[4:5], 0x58
	s_load_dwordx2 s[8:9], s[4:5], 0xa0
	s_load_dwordx2 s[10:11], s[4:5], 0xe0
	s_cmp_gt_u32 s15, 11
	s_cselect_b32 s15, 1, 0
	s_mov_b32 s40, 32768
	s_mov_b32 s41, 36864
	s_cselect_b32 s14, s40, s41
	v_and_b32_e32 v150, 63, v196
	v_lshrrev_b32_e32 v151, 6, v196
	s_nop 0
	v_readfirstlane_b32 s40, v151
	s_lshl_b32 s12, s12, 2
	s_add_i32 s12, s12, s40
	s_lshl_b32 s13, s13, 2
	v_lshlrev_b32_e32 v130, 4, v150
	v_lshrrev_b32_e32 v132, 3, v150
	v_lshlrev_b32_e32 v132, 2, v132
	s_mov_b32 s72, 0xffff
	s_mov_b32 s73, 0
	s_waitcnt lgkmcnt(0)
	s_mul_i32 s40, s15, 7680
	s_add_u32 s42, s6, s40
	s_addc_u32 s43, s7, 0
	v_lshlrev_b32_e32 v151, 5, v150
	s_add_u32 s44, s42, 0x1000
	s_addc_u32 s45, s43, 0
	global_load_dwordx4 v[106:109], v151, s[44:45]
	global_load_dwordx4 v[110:113], v151, s[44:45] offset:16
	s_add_u32 s44, s42, 0x1c00
	s_addc_u32 s45, s43, 0
	v_and_b32_e32 v152, 0x1ff, v151
	global_load_dwordx4 v[122:125], v152, s[44:45]
	global_load_dwordx4 v[126:129], v152, s[44:45] offset:16
	s_lshl_b32 s40, s15, 11
	s_add_u32 s42, s8, s40
	s_addc_u32 s43, s9, 0
	global_load_dwordx4 v[114:117], v151, s[42:43]
	global_load_dwordx4 v[118:121], v151, s[42:43] offset:16
	s_add_u32 s16, s10, 0x14360000
	s_addc_u32 s17, s11, 0
	s_add_u32 s18, s10, 0x6b60000
	s_addc_u32 s19, s11, 0
	s_add_u32 s20, s10, 0x8f60000
	s_addc_u32 s21, s11, 0
	s_add_u32 s22, s10, 0x1db2c000
	s_addc_u32 s23, s11, 0
	s_add_u32 s24, s10, 0x1dc4c000
	s_addc_u32 s25, s11, 0
	s_add_u32 s26, s10, 0xb360000
	s_addc_u32 s27, s11, 0
	s_add_u32 s28, s10, 0xd760000
	s_addc_u32 s29, s11, 0
	s_waitcnt vmcnt(0)
	s_cmp_lt_u32 s12, s14
	s_cbranch_scc0 .Lp1_exit
; DI float bf2f(u16 v) { return __uint_as_float(((unsigned)v) << 16); }
; DI int shift_nbr(int row, int col) {
;   if (row < NL) {
;     const int t = row & 2047, tc = t & 63, tr = t >> 6;
;     switch (col & 3) {
;       case 0: return tc > 0 ? row - 1 : -1;
;       case 1: return tc < 63 ? row + 1 : -1;
;       case 2: return tr > 0 ? row - 64 : -1;
;       default: return tr < 31 ? row + 64 : -1;
;     }
;   } else {
;     const int t = (row - NL) & 255;
;     if ((col & 1) == 0) return t > 0 ? row - 1 : -1;
;     return t < 255 ? row + 1 : -1;
;   }
; }
; DI float zshift(const u16* __restrict__ Z, int row, int nrow, int col, float mu) {
;   const float v = bf2f(Z[(size_t)row * RWB + col]);
;   const float nv = nrow >= 0 ? bf2f(Z[(size_t)nrow * RWB + col]) : 0.f;
;   return v + mu * (nv - v);
; }
; DI void post1_rows(const Params& p, int l, int nrows, int bid, int nb) {
;     ...
;   for (int row = bid * 4 + wid; row < nrows; row += nw) {
;     const int nrow = shift_nbr(row, lane);
;     float yv[8], vsv[8], bonv[8];
; #pragma unroll
;     for (int hh = 0; hh < 8; ++hh) {
;       const int col = hh * 64 + lane;
;       yv[hh] = bf2f(YF[(size_t)row * 512 + col]) + bf2f(YB[(size_t)row * 512 + col]);
;       bonv[hh] = BF[(size_t)row * 8 + hh] + BB[(size_t)row * 8 + hh];
;       vsv[hh] = zshift(Z, row, nrow, 1024 + col, mu[1024 + col]);
;     }
	s_cmp_lt_u32 s12, 32768
	s_cselect_b32 s47, 1, 0
	s_sub_u32 s40, s12, 32768
	s_and_b32 s40, s40, 255
	s_and_b32 s41, s12, 63
	s_bfe_u32 s42, s12, 0x50006
	s_cmp_eq_u32 s47, 1
	s_cselect_b32 s43, s41, s40
	s_cselect_b32 s44, 63, 255
	s_cselect_b32 s45, s42, s40
	s_cselect_b32 s46, 31, 255
	s_cselect_b32 s41, s41, s40
	s_cselect_b32 s42, s42, s40
	s_cselect_b32 s40, 64, 1
	s_cmp_gt_u32 s43, 0
	s_cselect_b32 s48, 0xffff, 0
	s_cmp_lt_u32 s41, s44
	s_cselect_b32 s53, 0xffff0000, 0
	s_cmp_gt_u32 s45, 0
	s_cselect_b32 s50, 0xffff, 0
	s_cmp_lt_u32 s42, s46
	s_cselect_b32 s55, 0xffff0000, 0
	s_mul_i32 s41, s12, 3840
	s_add_u32 s30, s16, s41
	s_addc_u32 s31, s17, 0
	s_mov_b32 s42, -3840
	s_cmp_lg_u32 s48, 0
	s_cselect_b32 s42, s42, 0
	s_ashr_i32 s43, s42, 31
	s_add_u32 s32, s30, s42
	s_addc_u32 s33, s31, s43
	s_mov_b32 s42, 3840
	s_cmp_lg_u32 s53, 0
	s_cselect_b32 s42, s42, 0
	s_ashr_i32 s43, s42, 31
	s_add_u32 s34, s30, s42
	s_addc_u32 s35, s31, s43
	s_mul_i32 s42, s40, -3840
	s_cmp_lg_u32 s50, 0
	s_cselect_b32 s42, s42, 0
	s_ashr_i32 s43, s42, 31
	s_add_u32 s36, s30, s42
	s_addc_u32 s37, s31, s43
	s_mul_i32 s42, s40, 3840
	s_cmp_lg_u32 s55, 0
	s_cselect_b32 s42, s42, 0
	s_ashr_i32 s43, s42, 31
	s_add_u32 s38, s30, s42
	s_addc_u32 s39, s31, s43
	s_lshl_b32 s41, s12, 10
	s_add_u32 s42, s18, s41
	s_addc_u32 s43, s19, 0
	global_load_dwordx4 v[6:9], v130, s[42:43]
	s_add_u32 s42, s20, s41
	s_addc_u32 s43, s21, 0
	global_load_dwordx4 v[10:13], v130, s[42:43]
	global_load_dwordx4 v[14:17], v130, s[30:31] offset:2048
	global_load_dwordx4 v[18:21], v130, s[32:33] offset:2048
	global_load_dwordx4 v[22:25], v130, s[34:35] offset:2048
	global_load_dwordx4 v[26:29], v130, s[36:37] offset:2048
	global_load_dwordx4 v[30:33], v130, s[38:39] offset:2048
	s_lshl_b32 s41, s12, 5
	s_add_u32 s42, s22, s41
	s_addc_u32 s43, s23, 0
	global_load_dword v34, v132, s[42:43]
	s_add_u32 s42, s24, s41
	s_addc_u32 s43, s25, 0
	global_load_dword v35, v132, s[42:43]
	s_mov_b64 exec, s[72:73]
	global_load_dwordx4 v[36:39], v130, s[30:31] offset:3584
	global_load_dwordx4 v[40:43], v130, s[32:33] offset:3584
	global_load_dwordx4 v[44:47], v130, s[34:35] offset:3584
	global_load_dwordx4 v[48:51], v130, s[36:37] offset:3584
	global_load_dwordx4 v[52:55], v130, s[38:39] offset:3584
	s_mov_b64 exec, -1
	s_mov_b32 s64, s48
	s_mov_b32 s65, s53
	s_mov_b32 s66, s50
	s_mov_b32 s67, s55
	s_mov_b32 s74, s12
.Lp1_loop:
	s_add_u32 s12, s12, s13
	s_cmp_lt_u32 s12, s14
	s_cbranch_scc0 .Lp1_last0
	s_cmp_lt_u32 s12, 32768
	s_cselect_b32 s47, 1, 0
	s_sub_u32 s40, s12, 32768
	s_and_b32 s40, s40, 255
	s_and_b32 s41, s12, 63
	s_bfe_u32 s42, s12, 0x50006
	s_cmp_eq_u32 s47, 1
	s_cselect_b32 s43, s41, s40
	s_cselect_b32 s44, 63, 255
	s_cselect_b32 s45, s42, s40
	s_cselect_b32 s46, 31, 255
	s_cselect_b32 s41, s41, s40
	s_cselect_b32 s42, s42, s40
	s_cselect_b32 s40, 64, 1
	s_cmp_gt_u32 s43, 0
	s_cselect_b32 s48, 0xffff, 0
	s_cmp_lt_u32 s41, s44
	s_cselect_b32 s53, 0xffff0000, 0
	s_cmp_gt_u32 s45, 0
	s_cselect_b32 s50, 0xffff, 0
	s_cmp_lt_u32 s42, s46
	s_cselect_b32 s55, 0xffff0000, 0
	s_mul_i32 s41, s12, 3840
	s_add_u32 s30, s16, s41
	s_addc_u32 s31, s17, 0
	s_mov_b32 s42, -3840
	s_cmp_lg_u32 s48, 0
	s_cselect_b32 s42, s42, 0
	s_ashr_i32 s43, s42, 31
	s_add_u32 s32, s30, s42
	s_addc_u32 s33, s31, s43
	s_mov_b32 s42, 3840
	s_cmp_lg_u32 s53, 0
	s_cselect_b32 s42, s42, 0
	s_ashr_i32 s43, s42, 31
	s_add_u32 s34, s30, s42
	s_addc_u32 s35, s31, s43
	s_mul_i32 s42, s40, -3840
	s_cmp_lg_u32 s50, 0
	s_cselect_b32 s42, s42, 0
	s_ashr_i32 s43, s42, 31
	s_add_u32 s36, s30, s42
	s_addc_u32 s37, s31, s43
	s_mul_i32 s42, s40, 3840
	s_cmp_lg_u32 s55, 0
	s_cselect_b32 s42, s42, 0
	s_ashr_i32 s43, s42, 31
	s_add_u32 s38, s30, s42
	s_addc_u32 s39, s31, s43
	s_lshl_b32 s41, s12, 10
	s_add_u32 s42, s18, s41
	s_addc_u32 s43, s19, 0
	global_load_dwordx4 v[56:59], v130, s[42:43]
	s_add_u32 s42, s20, s41
	s_addc_u32 s43, s21, 0
	global_load_dwordx4 v[60:63], v130, s[42:43]
	global_load_dwordx4 v[64:67], v130, s[30:31] offset:2048
	global_load_dwordx4 v[68:71], v130, s[32:33] offset:2048
	global_load_dwordx4 v[72:75], v130, s[34:35] offset:2048
	global_load_dwordx4 v[76:79], v130, s[36:37] offset:2048
	global_load_dwordx4 v[80:83], v130, s[38:39] offset:2048
	s_lshl_b32 s41, s12, 5
	s_add_u32 s42, s22, s41
	s_addc_u32 s43, s23, 0
	global_load_dword v84, v132, s[42:43]
	s_add_u32 s42, s24, s41
	s_addc_u32 s43, s25, 0
	global_load_dword v85, v132, s[42:43]
	s_mov_b64 exec, s[72:73]
	global_load_dwordx4 v[86:89], v130, s[30:31] offset:3584
	global_load_dwordx4 v[90:93], v130, s[32:33] offset:3584
	global_load_dwordx4 v[94:97], v130, s[34:35] offset:3584
	global_load_dwordx4 v[98:101], v130, s[36:37] offset:3584
	global_load_dwordx4 v[102:105], v130, s[38:39] offset:3584
	s_mov_b64 exec, -1
	s_mov_b32 s68, s48
	s_mov_b32 s69, s53
	s_mov_b32 s70, s50
	s_mov_b32 s71, s55
	s_mov_b32 s75, s12
	s_waitcnt vmcnt(14)
; DI float bf2f(u16 v) { return __uint_as_float(((unsigned)v) << 16); }
; DI float sigmoidf_(float x) { return frcp(1.f + __expf(-x)); }
; DI void post1_rows(const Params& p, int l, int nrows, int bid, int nb) {
;     ...
;     for (int hh = 0; hh < 8; ++hh) {
;       const int col = hh * 64 + lane;
;       yv[hh] = bf2f(YF[(size_t)row * 512 + col]) + bf2f(YB[(size_t)row * 512 + col]);
;       bonv[hh] = BF[(size_t)row * 8 + hh] + BB[(size_t)row * 8 + hh];
;       vsv[hh] = zshift(Z, row, nrow, 1024 + col, mu[1024 + col]);
;     }
; #pragma unroll
;     for (int hh = 0; hh < 8; ++hh) {
;       const int col = hh * 64 + lane;
;       const float y = yv[hh];
;       const float mean = wave_sum_dpp(y) * (1.f / 64.f);
;       const float d = y - mean;
;       const float var = wave_sum_dpp(d * d) * (1.f / 64.f);
;       float o = d * rsqrtf(var + 64e-5f) * ng[col];
;       o += bonv[hh] * vsv[hh];
;       U[(size_t)row * 512 + col] = f2bf(o);
;     }
; #pragma unroll
;     for (int jj = 0; jj < 2; ++jj) {
;       const int col = 1792 + jj * 64 + lane;
;       const float zg = zshift(Z, row, nrow, col, mu[col]);
;       SG[(size_t)row * 128 + jj * 64 + lane] = f2bf(sigmoidf_(zg));
	v_and_b32_e32 v150, s64, v18
	v_and_or_b32 v160, v22, s65, v150
	v_and_b32_e32 v151, s66, v27
	v_and_or_b32 v161, v31, s67, v151
	v_and_b32_e32 v150, s64, v20
	v_and_or_b32 v162, v24, s65, v150
	v_and_b32_e32 v151, s66, v29
	v_and_or_b32 v163, v33, s67, v151
	v_lshlrev_b32_e32 v152, 16, v6
	v_and_b32_e32 v153, 0xffff0000, v6
	v_lshlrev_b32_e32 v154, 16, v10
	v_and_b32_e32 v155, 0xffff0000, v10
	v_add_f32_e32 v134, v152, v154
	v_add_f32_e32 v135, v153, v155
	v_lshlrev_b32_e32 v152, 16, v14
	v_and_b32_e32 v153, 0xffff0000, v14
	v_lshlrev_b32_e32 v154, 16, v160
	v_and_b32_e32 v155, 0xffff0000, v160
	v_sub_f32_e32 v154, v154, v152
	v_sub_f32_e32 v155, v155, v153
	v_fma_f32 v142, v106, v154, v152
	v_fma_f32 v143, v107, v155, v153
	v_lshlrev_b32_e32 v152, 16, v7
	v_and_b32_e32 v153, 0xffff0000, v7
	v_lshlrev_b32_e32 v154, 16, v11
	v_and_b32_e32 v155, 0xffff0000, v11
	v_add_f32_e32 v136, v152, v154
	v_add_f32_e32 v137, v153, v155
	v_lshlrev_b32_e32 v152, 16, v15
	v_and_b32_e32 v153, 0xffff0000, v15
	v_lshlrev_b32_e32 v154, 16, v161
	v_and_b32_e32 v155, 0xffff0000, v161
	v_sub_f32_e32 v154, v154, v152
	v_sub_f32_e32 v155, v155, v153
	v_fma_f32 v144, v108, v154, v152
	v_fma_f32 v145, v109, v155, v153
	v_lshlrev_b32_e32 v152, 16, v8
	v_and_b32_e32 v153, 0xffff0000, v8
	v_lshlrev_b32_e32 v154, 16, v12
	v_and_b32_e32 v155, 0xffff0000, v12
	v_add_f32_e32 v138, v152, v154
	v_add_f32_e32 v139, v153, v155
	v_lshlrev_b32_e32 v152, 16, v16
	v_and_b32_e32 v153, 0xffff0000, v16
	v_lshlrev_b32_e32 v154, 16, v162
	v_and_b32_e32 v155, 0xffff0000, v162
	v_sub_f32_e32 v154, v154, v152
	v_sub_f32_e32 v155, v155, v153
	v_fma_f32 v146, v110, v154, v152
	v_fma_f32 v147, v111, v155, v153
	v_lshlrev_b32_e32 v152, 16, v9
	v_and_b32_e32 v153, 0xffff0000, v9
	v_lshlrev_b32_e32 v154, 16, v13
	v_and_b32_e32 v155, 0xffff0000, v13
	v_add_f32_e32 v140, v152, v154
	v_add_f32_e32 v141, v153, v155
	v_lshlrev_b32_e32 v152, 16, v17
	v_and_b32_e32 v153, 0xffff0000, v17
	v_lshlrev_b32_e32 v154, 16, v163
	v_and_b32_e32 v155, 0xffff0000, v163
	v_sub_f32_e32 v154, v154, v152
	v_sub_f32_e32 v155, v155, v153
	v_fma_f32 v148, v112, v154, v152
	v_fma_f32 v149, v113, v155, v153
	v_add_f32_e32 v156, v134, v135
	v_add_f32_e32 v156, v156, v136
	v_add_f32_e32 v156, v156, v137
	v_add_f32_e32 v156, v156, v138
	v_add_f32_e32 v156, v156, v139
	v_add_f32_e32 v156, v156, v140
	v_add_f32_e32 v156, v156, v141
	v_add_f32_e32 v157, v34, v35
	s_nop 0
	v_add_f32_dpp v156, v156, v156 quad_perm:[1,0,3,2] row_mask:0xf bank_mask:0xf bound_ctrl:1
	s_nop 1
	v_add_f32_dpp v156, v156, v156 quad_perm:[2,3,0,1] row_mask:0xf bank_mask:0xf bound_ctrl:1
	s_nop 1
	v_add_f32_dpp v156, v156, v156 row_half_mirror row_mask:0xf bank_mask:0xf bound_ctrl:1
	v_mul_f32_e32 v156, 0x3c800000, v156
	v_sub_f32_e32 v134, v134, v156
	v_sub_f32_e32 v135, v135, v156
	v_sub_f32_e32 v136, v136, v156
	v_sub_f32_e32 v137, v137, v156
	v_sub_f32_e32 v138, v138, v156
	v_sub_f32_e32 v139, v139, v156
	v_sub_f32_e32 v140, v140, v156
	v_sub_f32_e32 v141, v141, v156
	v_mul_f32_e32 v158, v134, v134
	v_fmac_f32_e32 v158, v135, v135
	v_fmac_f32_e32 v158, v136, v136
	v_fmac_f32_e32 v158, v137, v137
	v_fmac_f32_e32 v158, v138, v138
	v_fmac_f32_e32 v158, v139, v139
	v_fmac_f32_e32 v158, v140, v140
	v_fmac_f32_e32 v158, v141, v141
	s_nop 1
	v_add_f32_dpp v158, v158, v158 quad_perm:[1,0,3,2] row_mask:0xf bank_mask:0xf bound_ctrl:1
	s_nop 1
	v_add_f32_dpp v158, v158, v158 quad_perm:[2,3,0,1] row_mask:0xf bank_mask:0xf bound_ctrl:1
	s_nop 1
	v_add_f32_dpp v158, v158, v158 row_half_mirror row_mask:0xf bank_mask:0xf bound_ctrl:1
	v_mul_f32_e32 v158, 0x3c800000, v158
	v_add_f32_e32 v158, 0x3a27c5ac, v158
	v_rsq_f32_e32 v158, v158
	s_nop 0
	v_mul_f32_e32 v134, v134, v158
	v_mul_f32_e32 v135, v135, v158
	v_mul_f32_e32 v136, v136, v158
	v_mul_f32_e32 v137, v137, v158
	v_mul_f32_e32 v138, v138, v158
	v_mul_f32_e32 v139, v139, v158
	v_mul_f32_e32 v140, v140, v158
	v_mul_f32_e32 v141, v141, v158
	v_mul_f32_e32 v142, v142, v157
	v_mul_f32_e32 v143, v143, v157
	v_mul_f32_e32 v144, v144, v157
	v_mul_f32_e32 v145, v145, v157
	v_mul_f32_e32 v146, v146, v157
	v_mul_f32_e32 v147, v147, v157
	v_mul_f32_e32 v148, v148, v157
	v_mul_f32_e32 v149, v149, v157
	v_fmac_f32_e32 v142, v134, v114
	v_fmac_f32_e32 v143, v135, v115
	v_fmac_f32_e32 v144, v136, v116
	v_fmac_f32_e32 v145, v137, v117
	v_fmac_f32_e32 v146, v138, v118
	v_fmac_f32_e32 v147, v139, v119
	v_fmac_f32_e32 v148, v140, v120
	v_fmac_f32_e32 v149, v141, v121
	v_cvt_pk_bf16_f32 v164, v142, v143
	v_cvt_pk_bf16_f32 v165, v144, v145
	v_cvt_pk_bf16_f32 v166, v146, v147
	v_cvt_pk_bf16_f32 v167, v148, v149
	s_lshl_b32 s41, s74, 10
	s_add_u32 s42, s26, s41
	s_addc_u32 s43, s27, 0
	global_store_dwordx4 v130, v[164:167], s[42:43]
	v_and_b32_e32 v150, s64, v40
	v_and_or_b32 v160, v44, s65, v150
	v_and_b32_e32 v151, s66, v49
	v_and_or_b32 v161, v53, s67, v151
	v_and_b32_e32 v150, s64, v42
	v_and_or_b32 v162, v46, s65, v150
	v_and_b32_e32 v151, s66, v51
	v_and_or_b32 v163, v55, s67, v151
	v_lshlrev_b32_e32 v152, 16, v36
	v_and_b32_e32 v153, 0xffff0000, v36
	v_lshlrev_b32_e32 v154, 16, v160
	v_and_b32_e32 v155, 0xffff0000, v160
	v_sub_f32_e32 v154, v154, v152
	v_sub_f32_e32 v155, v155, v153
	v_fma_f32 v134, v122, v154, v152
	v_fma_f32 v135, v123, v155, v153
	v_lshlrev_b32_e32 v152, 16, v37
	v_and_b32_e32 v153, 0xffff0000, v37
	v_lshlrev_b32_e32 v154, 16, v161
	v_and_b32_e32 v155, 0xffff0000, v161
	v_sub_f32_e32 v154, v154, v152
	v_sub_f32_e32 v155, v155, v153
	v_fma_f32 v136, v124, v154, v152
	v_fma_f32 v137, v125, v155, v153
	v_lshlrev_b32_e32 v152, 16, v38
	v_and_b32_e32 v153, 0xffff0000, v38
	v_lshlrev_b32_e32 v154, 16, v162
; DI float sigmoidf_(float x) { return frcp(1.f + __expf(-x)); }
; DI void post1_rows(const Params& p, int l, int nrows, int bid, int nb) {
;     ...
; #pragma unroll
;     for (int jj = 0; jj < 2; ++jj) {
;       const int col = 1792 + jj * 64 + lane;
;       const float zg = zshift(Z, row, nrow, col, mu[col]);
;       SG[(size_t)row * 128 + jj * 64 + lane] = f2bf(sigmoidf_(zg));
;     }
;   }
	v_and_b32_e32 v155, 0xffff0000, v162
	v_sub_f32_e32 v154, v154, v152
	v_sub_f32_e32 v155, v155, v153
	v_fma_f32 v138, v126, v154, v152
	v_fma_f32 v139, v127, v155, v153
	v_lshlrev_b32_e32 v152, 16, v39
	v_and_b32_e32 v153, 0xffff0000, v39
	v_lshlrev_b32_e32 v154, 16, v163
	v_and_b32_e32 v155, 0xffff0000, v163
	v_sub_f32_e32 v154, v154, v152
	v_sub_f32_e32 v155, v155, v153
	v_fma_f32 v140, v128, v154, v152
	v_fma_f32 v141, v129, v155, v153
	v_mul_f32_e32 v134, 0xbfb8aa3b, v134
	v_mul_f32_e32 v135, 0xbfb8aa3b, v135
	v_mul_f32_e32 v136, 0xbfb8aa3b, v136
	v_mul_f32_e32 v137, 0xbfb8aa3b, v137
	v_mul_f32_e32 v138, 0xbfb8aa3b, v138
	v_mul_f32_e32 v139, 0xbfb8aa3b, v139
	v_mul_f32_e32 v140, 0xbfb8aa3b, v140
	v_mul_f32_e32 v141, 0xbfb8aa3b, v141
	v_exp_f32_e32 v134, v134
	v_exp_f32_e32 v135, v135
	v_exp_f32_e32 v136, v136
	v_exp_f32_e32 v137, v137
	v_exp_f32_e32 v138, v138
	v_exp_f32_e32 v139, v139
	v_exp_f32_e32 v140, v140
	v_exp_f32_e32 v141, v141
	s_nop 0
	v_add_f32_e32 v134, 1.0, v134
	v_add_f32_e32 v135, 1.0, v135
	v_add_f32_e32 v136, 1.0, v136
	v_add_f32_e32 v137, 1.0, v137
	v_add_f32_e32 v138, 1.0, v138
	v_add_f32_e32 v139, 1.0, v139
	v_add_f32_e32 v140, 1.0, v140
	v_add_f32_e32 v141, 1.0, v141
	v_rcp_f32_e32 v134, v134
	v_rcp_f32_e32 v135, v135
	v_rcp_f32_e32 v136, v136
	v_rcp_f32_e32 v137, v137
	v_rcp_f32_e32 v138, v138
	v_rcp_f32_e32 v139, v139
	v_rcp_f32_e32 v140, v140
	v_rcp_f32_e32 v141, v141
	s_nop 0
	v_cvt_pk_bf16_f32 v164, v134, v135
	v_cvt_pk_bf16_f32 v165, v136, v137
	v_cvt_pk_bf16_f32 v166, v138, v139
	v_cvt_pk_bf16_f32 v167, v140, v141
	s_lshl_b32 s41, s74, 8
	s_add_u32 s42, s28, s41
	s_addc_u32 s43, s29, 0
	s_mov_b64 exec, s[72:73]
	global_store_dwordx4 v130, v[164:167], s[42:43]
	s_mov_b64 exec, -1
	s_add_u32 s12, s12, s13
	s_cmp_lt_u32 s12, s14
	s_cbranch_scc0 .Lp1_last1
	s_cmp_lt_u32 s12, 32768
	s_cselect_b32 s47, 1, 0
	s_sub_u32 s40, s12, 32768
	s_and_b32 s40, s40, 255
	s_and_b32 s41, s12, 63
	s_bfe_u32 s42, s12, 0x50006
	s_cmp_eq_u32 s47, 1
	s_cselect_b32 s43, s41, s40
	s_cselect_b32 s44, 63, 255
	s_cselect_b32 s45, s42, s40
	s_cselect_b32 s46, 31, 255
	s_cselect_b32 s41, s41, s40
	s_cselect_b32 s42, s42, s40
	s_cselect_b32 s40, 64, 1
	s_cmp_gt_u32 s43, 0
	s_cselect_b32 s48, 0xffff, 0
	s_cmp_lt_u32 s41, s44
	s_cselect_b32 s53, 0xffff0000, 0
	s_cmp_gt_u32 s45, 0
	s_cselect_b32 s50, 0xffff, 0
	s_cmp_lt_u32 s42, s46
	s_cselect_b32 s55, 0xffff0000, 0
	s_mul_i32 s41, s12, 3840
	s_add_u32 s30, s16, s41
	s_addc_u32 s31, s17, 0
	s_mov_b32 s42, -3840
	s_cmp_lg_u32 s48, 0
	s_cselect_b32 s42, s42, 0
	s_ashr_i32 s43, s42, 31
	s_add_u32 s32, s30, s42
	s_addc_u32 s33, s31, s43
	s_mov_b32 s42, 3840
	s_cmp_lg_u32 s53, 0
	s_cselect_b32 s42, s42, 0
	s_ashr_i32 s43, s42, 31
	s_add_u32 s34, s30, s42
	s_addc_u32 s35, s31, s43
	s_mul_i32 s42, s40, -3840
	s_cmp_lg_u32 s50, 0
	s_cselect_b32 s42, s42, 0
	s_ashr_i32 s43, s42, 31
	s_add_u32 s36, s30, s42
	s_addc_u32 s37, s31, s43
	s_mul_i32 s42, s40, 3840
	s_cmp_lg_u32 s55, 0
	s_cselect_b32 s42, s42, 0
	s_ashr_i32 s43, s42, 31
	s_add_u32 s38, s30, s42
	s_addc_u32 s39, s31, s43
	s_lshl_b32 s41, s12, 10
	s_add_u32 s42, s18, s41
	s_addc_u32 s43, s19, 0
	global_load_dwordx4 v[6:9], v130, s[42:43]
	s_add_u32 s42, s20, s41
	s_addc_u32 s43, s21, 0
	global_load_dwordx4 v[10:13], v130, s[42:43]
	global_load_dwordx4 v[14:17], v130, s[30:31] offset:2048
	global_load_dwordx4 v[18:21], v130, s[32:33] offset:2048
	global_load_dwordx4 v[22:25], v130, s[34:35] offset:2048
	global_load_dwordx4 v[26:29], v130, s[36:37] offset:2048
	global_load_dwordx4 v[30:33], v130, s[38:39] offset:2048
	s_lshl_b32 s41, s12, 5
	s_add_u32 s42, s22, s41
	s_addc_u32 s43, s23, 0
	global_load_dword v34, v132, s[42:43]
	s_add_u32 s42, s24, s41
	s_addc_u32 s43, s25, 0
	global_load_dword v35, v132, s[42:43]
	s_mov_b64 exec, s[72:73]
	global_load_dwordx4 v[36:39], v130, s[30:31] offset:3584
	global_load_dwordx4 v[40:43], v130, s[32:33] offset:3584
	global_load_dwordx4 v[44:47], v130, s[34:35] offset:3584
	global_load_dwordx4 v[48:51], v130, s[36:37] offset:3584
	global_load_dwordx4 v[52:55], v130, s[38:39] offset:3584
	s_mov_b64 exec, -1
	s_mov_b32 s64, s48
	s_mov_b32 s65, s53
	s_mov_b32 s66, s50
	s_mov_b32 s67, s55
	s_mov_b32 s74, s12
	s_waitcnt vmcnt(14)
; DI float bf2f(u16 v) { return __uint_as_float(((unsigned)v) << 16); }
; DI float sigmoidf_(float x) { return frcp(1.f + __expf(-x)); }
; DI void post1_rows(const Params& p, int l, int nrows, int bid, int nb) {
;     ...
;     for (int hh = 0; hh < 8; ++hh) {
;       const int col = hh * 64 + lane;
;       yv[hh] = bf2f(YF[(size_t)row * 512 + col]) + bf2f(YB[(size_t)row * 512 + col]);
;       bonv[hh] = BF[(size_t)row * 8 + hh] + BB[(size_t)row * 8 + hh];
;       vsv[hh] = zshift(Z, row, nrow, 1024 + col, mu[1024 + col]);
;     }
; #pragma unroll
;     for (int hh = 0; hh < 8; ++hh) {
;       const int col = hh * 64 + lane;
;       const float y = yv[hh];
;       const float mean = wave_sum_dpp(y) * (1.f / 64.f);
;       const float d = y - mean;
;       const float var = wave_sum_dpp(d * d) * (1.f / 64.f);
;       float o = d * rsqrtf(var + 64e-5f) * ng[col];
;       o += bonv[hh] * vsv[hh];
;       U[(size_t)row * 512 + col] = f2bf(o);
;     }
; #pragma unroll
;     for (int jj = 0; jj < 2; ++jj) {
;       const int col = 1792 + jj * 64 + lane;
;       const float zg = zshift(Z, row, nrow, col, mu[col]);
;       SG[(size_t)row * 128 + jj * 64 + lane] = f2bf(sigmoidf_(zg));
	v_and_b32_e32 v150, s68, v68
	v_and_or_b32 v160, v72, s69, v150
	v_and_b32_e32 v151, s70, v77
	v_and_or_b32 v161, v81, s71, v151
	v_and_b32_e32 v150, s68, v70
	v_and_or_b32 v162, v74, s69, v150
	v_and_b32_e32 v151, s70, v79
	v_and_or_b32 v163, v83, s71, v151
	v_lshlrev_b32_e32 v152, 16, v56
	v_and_b32_e32 v153, 0xffff0000, v56
	v_lshlrev_b32_e32 v154, 16, v60
	v_and_b32_e32 v155, 0xffff0000, v60
	v_add_f32_e32 v134, v152, v154
	v_add_f32_e32 v135, v153, v155
	v_lshlrev_b32_e32 v152, 16, v64
	v_and_b32_e32 v153, 0xffff0000, v64
	v_lshlrev_b32_e32 v154, 16, v160
	v_and_b32_e32 v155, 0xffff0000, v160
	v_sub_f32_e32 v154, v154, v152
	v_sub_f32_e32 v155, v155, v153
	v_fma_f32 v142, v106, v154, v152
	v_fma_f32 v143, v107, v155, v153
	v_lshlrev_b32_e32 v152, 16, v57
	v_and_b32_e32 v153, 0xffff0000, v57
	v_lshlrev_b32_e32 v154, 16, v61
	v_and_b32_e32 v155, 0xffff0000, v61
	v_add_f32_e32 v136, v152, v154
	v_add_f32_e32 v137, v153, v155
	v_lshlrev_b32_e32 v152, 16, v65
	v_and_b32_e32 v153, 0xffff0000, v65
	v_lshlrev_b32_e32 v154, 16, v161
	v_and_b32_e32 v155, 0xffff0000, v161
	v_sub_f32_e32 v154, v154, v152
	v_sub_f32_e32 v155, v155, v153
	v_fma_f32 v144, v108, v154, v152
	v_fma_f32 v145, v109, v155, v153
	v_lshlrev_b32_e32 v152, 16, v58
	v_and_b32_e32 v153, 0xffff0000, v58
	v_lshlrev_b32_e32 v154, 16, v62
	v_and_b32_e32 v155, 0xffff0000, v62
	v_add_f32_e32 v138, v152, v154
	v_add_f32_e32 v139, v153, v155
	v_lshlrev_b32_e32 v152, 16, v66
	v_and_b32_e32 v153, 0xffff0000, v66
	v_lshlrev_b32_e32 v154, 16, v162
	v_and_b32_e32 v155, 0xffff0000, v162
	v_sub_f32_e32 v154, v154, v152
	v_sub_f32_e32 v155, v155, v153
	v_fma_f32 v146, v110, v154, v152
	v_fma_f32 v147, v111, v155, v153
	v_lshlrev_b32_e32 v152, 16, v59
	v_and_b32_e32 v153, 0xffff0000, v59
	v_lshlrev_b32_e32 v154, 16, v63
	v_and_b32_e32 v155, 0xffff0000, v63
	v_add_f32_e32 v140, v152, v154
	v_add_f32_e32 v141, v153, v155
	v_lshlrev_b32_e32 v152, 16, v67
	v_and_b32_e32 v153, 0xffff0000, v67
	v_lshlrev_b32_e32 v154, 16, v163
	v_and_b32_e32 v155, 0xffff0000, v163
	v_sub_f32_e32 v154, v154, v152
	v_sub_f32_e32 v155, v155, v153
	v_fma_f32 v148, v112, v154, v152
	v_fma_f32 v149, v113, v155, v153
	v_add_f32_e32 v156, v134, v135
	v_add_f32_e32 v156, v156, v136
	v_add_f32_e32 v156, v156, v137
	v_add_f32_e32 v156, v156, v138
	v_add_f32_e32 v156, v156, v139
	v_add_f32_e32 v156, v156, v140
	v_add_f32_e32 v156, v156, v141
	v_add_f32_e32 v157, v84, v85
	s_nop 0
	v_add_f32_dpp v156, v156, v156 quad_perm:[1,0,3,2] row_mask:0xf bank_mask:0xf bound_ctrl:1
	s_nop 1
	v_add_f32_dpp v156, v156, v156 quad_perm:[2,3,0,1] row_mask:0xf bank_mask:0xf bound_ctrl:1
	s_nop 1
	v_add_f32_dpp v156, v156, v156 row_half_mirror row_mask:0xf bank_mask:0xf bound_ctrl:1
	v_mul_f32_e32 v156, 0x3c800000, v156
	v_sub_f32_e32 v134, v134, v156
	v_sub_f32_e32 v135, v135, v156
	v_sub_f32_e32 v136, v136, v156
	v_sub_f32_e32 v137, v137, v156
	v_sub_f32_e32 v138, v138, v156
	v_sub_f32_e32 v139, v139, v156
	v_sub_f32_e32 v140, v140, v156
	v_sub_f32_e32 v141, v141, v156
	v_mul_f32_e32 v158, v134, v134
	v_fmac_f32_e32 v158, v135, v135
	v_fmac_f32_e32 v158, v136, v136
	v_fmac_f32_e32 v158, v137, v137
	v_fmac_f32_e32 v158, v138, v138
	v_fmac_f32_e32 v158, v139, v139
	v_fmac_f32_e32 v158, v140, v140
	v_fmac_f32_e32 v158, v141, v141
	s_nop 1
	v_add_f32_dpp v158, v158, v158 quad_perm:[1,0,3,2] row_mask:0xf bank_mask:0xf bound_ctrl:1
	s_nop 1
	v_add_f32_dpp v158, v158, v158 quad_perm:[2,3,0,1] row_mask:0xf bank_mask:0xf bound_ctrl:1
	s_nop 1
	v_add_f32_dpp v158, v158, v158 row_half_mirror row_mask:0xf bank_mask:0xf bound_ctrl:1
	v_mul_f32_e32 v158, 0x3c800000, v158
	v_add_f32_e32 v158, 0x3a27c5ac, v158
	v_rsq_f32_e32 v158, v158
	s_nop 0
	v_mul_f32_e32 v134, v134, v158
	v_mul_f32_e32 v135, v135, v158
	v_mul_f32_e32 v136, v136, v158
	v_mul_f32_e32 v137, v137, v158
	v_mul_f32_e32 v138, v138, v158
	v_mul_f32_e32 v139, v139, v158
	v_mul_f32_e32 v140, v140, v158
	v_mul_f32_e32 v141, v141, v158
	v_mul_f32_e32 v142, v142, v157
	v_mul_f32_e32 v143, v143, v157
	v_mul_f32_e32 v144, v144, v157
	v_mul_f32_e32 v145, v145, v157
	v_mul_f32_e32 v146, v146, v157
	v_mul_f32_e32 v147, v147, v157
	v_mul_f32_e32 v148, v148, v157
	v_mul_f32_e32 v149, v149, v157
	v_fmac_f32_e32 v142, v134, v114
	v_fmac_f32_e32 v143, v135, v115
	v_fmac_f32_e32 v144, v136, v116
	v_fmac_f32_e32 v145, v137, v117
	v_fmac_f32_e32 v146, v138, v118
	v_fmac_f32_e32 v147, v139, v119
	v_fmac_f32_e32 v148, v140, v120
	v_fmac_f32_e32 v149, v141, v121
	v_cvt_pk_bf16_f32 v164, v142, v143
	v_cvt_pk_bf16_f32 v165, v144, v145
	v_cvt_pk_bf16_f32 v166, v146, v147
	v_cvt_pk_bf16_f32 v167, v148, v149
	s_lshl_b32 s41, s75, 10
	s_add_u32 s42, s26, s41
	s_addc_u32 s43, s27, 0
	global_store_dwordx4 v130, v[164:167], s[42:43]
	v_and_b32_e32 v150, s68, v90
	v_and_or_b32 v160, v94, s69, v150
	v_and_b32_e32 v151, s70, v99
	v_and_or_b32 v161, v103, s71, v151
	v_and_b32_e32 v150, s68, v92
	v_and_or_b32 v162, v96, s69, v150
	v_and_b32_e32 v151, s70, v101
	v_and_or_b32 v163, v105, s71, v151
	v_lshlrev_b32_e32 v152, 16, v86
	v_and_b32_e32 v153, 0xffff0000, v86
	v_lshlrev_b32_e32 v154, 16, v160
	v_and_b32_e32 v155, 0xffff0000, v160
	v_sub_f32_e32 v154, v154, v152
	v_sub_f32_e32 v155, v155, v153
	v_fma_f32 v134, v122, v154, v152
	v_fma_f32 v135, v123, v155, v153
	v_lshlrev_b32_e32 v152, 16, v87
	v_and_b32_e32 v153, 0xffff0000, v87
	v_lshlrev_b32_e32 v154, 16, v161
	v_and_b32_e32 v155, 0xffff0000, v161
	v_sub_f32_e32 v154, v154, v152
	v_sub_f32_e32 v155, v155, v153
	v_fma_f32 v136, v124, v154, v152
	v_fma_f32 v137, v125, v155, v153
	v_lshlrev_b32_e32 v152, 16, v88
	v_and_b32_e32 v153, 0xffff0000, v88
	v_lshlrev_b32_e32 v154, 16, v162
; DI float sigmoidf_(float x) { return frcp(1.f + __expf(-x)); }
; DI void post1_rows(const Params& p, int l, int nrows, int bid, int nb) {
;     ...
; #pragma unroll
;     for (int jj = 0; jj < 2; ++jj) {
;       const int col = 1792 + jj * 64 + lane;
;       const float zg = zshift(Z, row, nrow, col, mu[col]);
;       SG[(size_t)row * 128 + jj * 64 + lane] = f2bf(sigmoidf_(zg));
;     }
;   }
	v_and_b32_e32 v155, 0xffff0000, v162
	v_sub_f32_e32 v154, v154, v152
	v_sub_f32_e32 v155, v155, v153
	v_fma_f32 v138, v126, v154, v152
	v_fma_f32 v139, v127, v155, v153
	v_lshlrev_b32_e32 v152, 16, v89
	v_and_b32_e32 v153, 0xffff0000, v89
	v_lshlrev_b32_e32 v154, 16, v163
	v_and_b32_e32 v155, 0xffff0000, v163
	v_sub_f32_e32 v154, v154, v152
	v_sub_f32_e32 v155, v155, v153
	v_fma_f32 v140, v128, v154, v152
	v_fma_f32 v141, v129, v155, v153
	v_mul_f32_e32 v134, 0xbfb8aa3b, v134
	v_mul_f32_e32 v135, 0xbfb8aa3b, v135
	v_mul_f32_e32 v136, 0xbfb8aa3b, v136
	v_mul_f32_e32 v137, 0xbfb8aa3b, v137
	v_mul_f32_e32 v138, 0xbfb8aa3b, v138
	v_mul_f32_e32 v139, 0xbfb8aa3b, v139
	v_mul_f32_e32 v140, 0xbfb8aa3b, v140
	v_mul_f32_e32 v141, 0xbfb8aa3b, v141
	v_exp_f32_e32 v134, v134
	v_exp_f32_e32 v135, v135
	v_exp_f32_e32 v136, v136
	v_exp_f32_e32 v137, v137
	v_exp_f32_e32 v138, v138
	v_exp_f32_e32 v139, v139
	v_exp_f32_e32 v140, v140
	v_exp_f32_e32 v141, v141
	s_nop 0
	v_add_f32_e32 v134, 1.0, v134
	v_add_f32_e32 v135, 1.0, v135
	v_add_f32_e32 v136, 1.0, v136
	v_add_f32_e32 v137, 1.0, v137
	v_add_f32_e32 v138, 1.0, v138
	v_add_f32_e32 v139, 1.0, v139
	v_add_f32_e32 v140, 1.0, v140
	v_add_f32_e32 v141, 1.0, v141
	v_rcp_f32_e32 v134, v134
	v_rcp_f32_e32 v135, v135
	v_rcp_f32_e32 v136, v136
	v_rcp_f32_e32 v137, v137
	v_rcp_f32_e32 v138, v138
	v_rcp_f32_e32 v139, v139
	v_rcp_f32_e32 v140, v140
	v_rcp_f32_e32 v141, v141
	s_nop 0
	v_cvt_pk_bf16_f32 v164, v134, v135
	v_cvt_pk_bf16_f32 v165, v136, v137
	v_cvt_pk_bf16_f32 v166, v138, v139
	v_cvt_pk_bf16_f32 v167, v140, v141
	s_lshl_b32 s41, s75, 8
	s_add_u32 s42, s28, s41
	s_addc_u32 s43, s29, 0
	s_mov_b64 exec, s[72:73]
	global_store_dwordx4 v130, v[164:167], s[42:43]
	s_mov_b64 exec, -1
	s_branch .Lp1_loop
.Lp1_last0:
	s_waitcnt vmcnt(0)
	v_and_b32_e32 v150, s64, v18
	v_and_or_b32 v160, v22, s65, v150
	v_and_b32_e32 v151, s66, v27
	v_and_or_b32 v161, v31, s67, v151
	v_and_b32_e32 v150, s64, v20
	v_and_or_b32 v162, v24, s65, v150
	v_and_b32_e32 v151, s66, v29
	v_and_or_b32 v163, v33, s67, v151
	v_lshlrev_b32_e32 v152, 16, v6
	v_and_b32_e32 v153, 0xffff0000, v6
	v_lshlrev_b32_e32 v154, 16, v10
	v_and_b32_e32 v155, 0xffff0000, v10
	v_add_f32_e32 v134, v152, v154
	v_add_f32_e32 v135, v153, v155
	v_lshlrev_b32_e32 v152, 16, v14
	v_and_b32_e32 v153, 0xffff0000, v14
	v_lshlrev_b32_e32 v154, 16, v160
	v_and_b32_e32 v155, 0xffff0000, v160
	v_sub_f32_e32 v154, v154, v152
	v_sub_f32_e32 v155, v155, v153
	v_fma_f32 v142, v106, v154, v152
	v_fma_f32 v143, v107, v155, v153
	v_lshlrev_b32_e32 v152, 16, v7
	v_and_b32_e32 v153, 0xffff0000, v7
	v_lshlrev_b32_e32 v154, 16, v11
	v_and_b32_e32 v155, 0xffff0000, v11
	v_add_f32_e32 v136, v152, v154
	v_add_f32_e32 v137, v153, v155
	v_lshlrev_b32_e32 v152, 16, v15
	v_and_b32_e32 v153, 0xffff0000, v15
	v_lshlrev_b32_e32 v154, 16, v161
	v_and_b32_e32 v155, 0xffff0000, v161
	v_sub_f32_e32 v154, v154, v152
	v_sub_f32_e32 v155, v155, v153
	v_fma_f32 v144, v108, v154, v152
	v_fma_f32 v145, v109, v155, v153
	v_lshlrev_b32_e32 v152, 16, v8
	v_and_b32_e32 v153, 0xffff0000, v8
	v_lshlrev_b32_e32 v154, 16, v12
	v_and_b32_e32 v155, 0xffff0000, v12
	v_add_f32_e32 v138, v152, v154
	v_add_f32_e32 v139, v153, v155
	v_lshlrev_b32_e32 v152, 16, v16
	v_and_b32_e32 v153, 0xffff0000, v16
	v_lshlrev_b32_e32 v154, 16, v162
	v_and_b32_e32 v155, 0xffff0000, v162
	v_sub_f32_e32 v154, v154, v152
	v_sub_f32_e32 v155, v155, v153
	v_fma_f32 v146, v110, v154, v152
	v_fma_f32 v147, v111, v155, v153
	v_lshlrev_b32_e32 v152, 16, v9
	v_and_b32_e32 v153, 0xffff0000, v9
	v_lshlrev_b32_e32 v154, 16, v13
	v_and_b32_e32 v155, 0xffff0000, v13
	v_add_f32_e32 v140, v152, v154
	v_add_f32_e32 v141, v153, v155
	v_lshlrev_b32_e32 v152, 16, v17
	v_and_b32_e32 v153, 0xffff0000, v17
	v_lshlrev_b32_e32 v154, 16, v163
	v_and_b32_e32 v155, 0xffff0000, v163
	v_sub_f32_e32 v154, v154, v152
	v_sub_f32_e32 v155, v155, v153
	v_fma_f32 v148, v112, v154, v152
	v_fma_f32 v149, v113, v155, v153
	v_add_f32_e32 v156, v134, v135
	v_add_f32_e32 v156, v156, v136
	v_add_f32_e32 v156, v156, v137
	v_add_f32_e32 v156, v156, v138
	v_add_f32_e32 v156, v156, v139
	v_add_f32_e32 v156, v156, v140
	v_add_f32_e32 v156, v156, v141
	v_add_f32_e32 v157, v34, v35
	s_nop 0
	v_add_f32_dpp v156, v156, v156 quad_perm:[1,0,3,2] row_mask:0xf bank_mask:0xf bound_ctrl:1
	s_nop 1
	v_add_f32_dpp v156, v156, v156 quad_perm:[2,3,0,1] row_mask:0xf bank_mask:0xf bound_ctrl:1
	s_nop 1
	v_add_f32_dpp v156, v156, v156 row_half_mirror row_mask:0xf bank_mask:0xf bound_ctrl:1
	v_mul_f32_e32 v156, 0x3c800000, v156
	v_sub_f32_e32 v134, v134, v156
	v_sub_f32_e32 v135, v135, v156
	v_sub_f32_e32 v136, v136, v156
	v_sub_f32_e32 v137, v137, v156
	v_sub_f32_e32 v138, v138, v156
	v_sub_f32_e32 v139, v139, v156
	v_sub_f32_e32 v140, v140, v156
	v_sub_f32_e32 v141, v141, v156
	v_mul_f32_e32 v158, v134, v134
	v_fmac_f32_e32 v158, v135, v135
	v_fmac_f32_e32 v158, v136, v136
	v_fmac_f32_e32 v158, v137, v137
	v_fmac_f32_e32 v158, v138, v138
	v_fmac_f32_e32 v158, v139, v139
	v_fmac_f32_e32 v158, v140, v140
	v_fmac_f32_e32 v158, v141, v141
	s_nop 1
	v_add_f32_dpp v158, v158, v158 quad_perm:[1,0,3,2] row_mask:0xf bank_mask:0xf bound_ctrl:1
	s_nop 1
	v_add_f32_dpp v158, v158, v158 quad_perm:[2,3,0,1] row_mask:0xf bank_mask:0xf bound_ctrl:1
	s_nop 1
	v_add_f32_dpp v158, v158, v158 row_half_mirror row_mask:0xf bank_mask:0xf bound_ctrl:1
	v_mul_f32_e32 v158, 0x3c800000, v158
	v_add_f32_e32 v158, 0x3a27c5ac, v158
	v_rsq_f32_e32 v158, v158
	s_nop 0
	v_mul_f32_e32 v134, v134, v158
	v_mul_f32_e32 v135, v135, v158
	v_mul_f32_e32 v136, v136, v158
	v_mul_f32_e32 v137, v137, v158
	v_mul_f32_e32 v138, v138, v158
; DI float sigmoidf_(float x) { return frcp(1.f + __expf(-x)); }
; DI void post1_rows(const Params& p, int l, int nrows, int bid, int nb) {
;     ...
; #pragma unroll
;     for (int hh = 0; hh < 8; ++hh) {
;       const int col = hh * 64 + lane;
;       const float y = yv[hh];
;       const float mean = wave_sum_dpp(y) * (1.f / 64.f);
;       const float d = y - mean;
;       const float var = wave_sum_dpp(d * d) * (1.f / 64.f);
;       float o = d * rsqrtf(var + 64e-5f) * ng[col];
;       o += bonv[hh] * vsv[hh];
;       U[(size_t)row * 512 + col] = f2bf(o);
;     }
; #pragma unroll
;     for (int jj = 0; jj < 2; ++jj) {
;       const int col = 1792 + jj * 64 + lane;
;       const float zg = zshift(Z, row, nrow, col, mu[col]);
;       SG[(size_t)row * 128 + jj * 64 + lane] = f2bf(sigmoidf_(zg));
;     }
	v_mul_f32_e32 v139, v139, v158
	v_mul_f32_e32 v140, v140, v158
	v_mul_f32_e32 v141, v141, v158
	v_mul_f32_e32 v142, v142, v157
	v_mul_f32_e32 v143, v143, v157
	v_mul_f32_e32 v144, v144, v157
	v_mul_f32_e32 v145, v145, v157
	v_mul_f32_e32 v146, v146, v157
	v_mul_f32_e32 v147, v147, v157
	v_mul_f32_e32 v148, v148, v157
	v_mul_f32_e32 v149, v149, v157
	v_fmac_f32_e32 v142, v134, v114
	v_fmac_f32_e32 v143, v135, v115
	v_fmac_f32_e32 v144, v136, v116
	v_fmac_f32_e32 v145, v137, v117
	v_fmac_f32_e32 v146, v138, v118
	v_fmac_f32_e32 v147, v139, v119
	v_fmac_f32_e32 v148, v140, v120
	v_fmac_f32_e32 v149, v141, v121
	v_cvt_pk_bf16_f32 v164, v142, v143
	v_cvt_pk_bf16_f32 v165, v144, v145
	v_cvt_pk_bf16_f32 v166, v146, v147
	v_cvt_pk_bf16_f32 v167, v148, v149
	s_lshl_b32 s41, s74, 10
	s_add_u32 s42, s26, s41
	s_addc_u32 s43, s27, 0
	global_store_dwordx4 v130, v[164:167], s[42:43]
	v_and_b32_e32 v150, s64, v40
	v_and_or_b32 v160, v44, s65, v150
	v_and_b32_e32 v151, s66, v49
	v_and_or_b32 v161, v53, s67, v151
	v_and_b32_e32 v150, s64, v42
	v_and_or_b32 v162, v46, s65, v150
	v_and_b32_e32 v151, s66, v51
	v_and_or_b32 v163, v55, s67, v151
	v_lshlrev_b32_e32 v152, 16, v36
	v_and_b32_e32 v153, 0xffff0000, v36
	v_lshlrev_b32_e32 v154, 16, v160
	v_and_b32_e32 v155, 0xffff0000, v160
	v_sub_f32_e32 v154, v154, v152
	v_sub_f32_e32 v155, v155, v153
	v_fma_f32 v134, v122, v154, v152
	v_fma_f32 v135, v123, v155, v153
	v_lshlrev_b32_e32 v152, 16, v37
	v_and_b32_e32 v153, 0xffff0000, v37
	v_lshlrev_b32_e32 v154, 16, v161
	v_and_b32_e32 v155, 0xffff0000, v161
	v_sub_f32_e32 v154, v154, v152
	v_sub_f32_e32 v155, v155, v153
	v_fma_f32 v136, v124, v154, v152
	v_fma_f32 v137, v125, v155, v153
	v_lshlrev_b32_e32 v152, 16, v38
	v_and_b32_e32 v153, 0xffff0000, v38
	v_lshlrev_b32_e32 v154, 16, v162
	v_and_b32_e32 v155, 0xffff0000, v162
	v_sub_f32_e32 v154, v154, v152
	v_sub_f32_e32 v155, v155, v153
	v_fma_f32 v138, v126, v154, v152
	v_fma_f32 v139, v127, v155, v153
	v_lshlrev_b32_e32 v152, 16, v39
	v_and_b32_e32 v153, 0xffff0000, v39
	v_lshlrev_b32_e32 v154, 16, v163
	v_and_b32_e32 v155, 0xffff0000, v163
	v_sub_f32_e32 v154, v154, v152
	v_sub_f32_e32 v155, v155, v153
	v_fma_f32 v140, v128, v154, v152
	v_fma_f32 v141, v129, v155, v153
	v_mul_f32_e32 v134, 0xbfb8aa3b, v134
	v_mul_f32_e32 v135, 0xbfb8aa3b, v135
	v_mul_f32_e32 v136, 0xbfb8aa3b, v136
	v_mul_f32_e32 v137, 0xbfb8aa3b, v137
	v_mul_f32_e32 v138, 0xbfb8aa3b, v138
	v_mul_f32_e32 v139, 0xbfb8aa3b, v139
	v_mul_f32_e32 v140, 0xbfb8aa3b, v140
	v_mul_f32_e32 v141, 0xbfb8aa3b, v141
	v_exp_f32_e32 v134, v134
	v_exp_f32_e32 v135, v135
	v_exp_f32_e32 v136, v136
	v_exp_f32_e32 v137, v137
	v_exp_f32_e32 v138, v138
	v_exp_f32_e32 v139, v139
	v_exp_f32_e32 v140, v140
	v_exp_f32_e32 v141, v141
	s_nop 0
	v_add_f32_e32 v134, 1.0, v134
	v_add_f32_e32 v135, 1.0, v135
	v_add_f32_e32 v136, 1.0, v136
	v_add_f32_e32 v137, 1.0, v137
	v_add_f32_e32 v138, 1.0, v138
	v_add_f32_e32 v139, 1.0, v139
	v_add_f32_e32 v140, 1.0, v140
	v_add_f32_e32 v141, 1.0, v141
	v_rcp_f32_e32 v134, v134
	v_rcp_f32_e32 v135, v135
	v_rcp_f32_e32 v136, v136
	v_rcp_f32_e32 v137, v137
	v_rcp_f32_e32 v138, v138
	v_rcp_f32_e32 v139, v139
	v_rcp_f32_e32 v140, v140
	v_rcp_f32_e32 v141, v141
	s_nop 0
	v_cvt_pk_bf16_f32 v164, v134, v135
	v_cvt_pk_bf16_f32 v165, v136, v137
	v_cvt_pk_bf16_f32 v166, v138, v139
	v_cvt_pk_bf16_f32 v167, v140, v141
	s_lshl_b32 s41, s74, 8
	s_add_u32 s42, s28, s41
	s_addc_u32 s43, s29, 0
	s_mov_b64 exec, s[72:73]
	global_store_dwordx4 v130, v[164:167], s[42:43]
	s_mov_b64 exec, -1
	s_branch .Lp1_exit
.Lp1_last1:
	s_waitcnt vmcnt(0)
	v_and_b32_e32 v150, s68, v68
	v_and_or_b32 v160, v72, s69, v150
	v_and_b32_e32 v151, s70, v77
	v_and_or_b32 v161, v81, s71, v151
	v_and_b32_e32 v150, s68, v70
	v_and_or_b32 v162, v74, s69, v150
	v_and_b32_e32 v151, s70, v79
	v_and_or_b32 v163, v83, s71, v151
	v_lshlrev_b32_e32 v152, 16, v56
	v_and_b32_e32 v153, 0xffff0000, v56
	v_lshlrev_b32_e32 v154, 16, v60
	v_and_b32_e32 v155, 0xffff0000, v60
	v_add_f32_e32 v134, v152, v154
	v_add_f32_e32 v135, v153, v155
	v_lshlrev_b32_e32 v152, 16, v64
	v_and_b32_e32 v153, 0xffff0000, v64
	v_lshlrev_b32_e32 v154, 16, v160
	v_and_b32_e32 v155, 0xffff0000, v160
	v_sub_f32_e32 v154, v154, v152
	v_sub_f32_e32 v155, v155, v153
	v_fma_f32 v142, v106, v154, v152
	v_fma_f32 v143, v107, v155, v153
	v_lshlrev_b32_e32 v152, 16, v57
	v_and_b32_e32 v153, 0xffff0000, v57
	v_lshlrev_b32_e32 v154, 16, v61
	v_and_b32_e32 v155, 0xffff0000, v61
	v_add_f32_e32 v136, v152, v154
	v_add_f32_e32 v137, v153, v155
	v_lshlrev_b32_e32 v152, 16, v65
	v_and_b32_e32 v153, 0xffff0000, v65
	v_lshlrev_b32_e32 v154, 16, v161
	v_and_b32_e32 v155, 0xffff0000, v161
	v_sub_f32_e32 v154, v154, v152
	v_sub_f32_e32 v155, v155, v153
	v_fma_f32 v144, v108, v154, v152
	v_fma_f32 v145, v109, v155, v153
	v_lshlrev_b32_e32 v152, 16, v58
	v_and_b32_e32 v153, 0xffff0000, v58
	v_lshlrev_b32_e32 v154, 16, v62
	v_and_b32_e32 v155, 0xffff0000, v62
	v_add_f32_e32 v138, v152, v154
	v_add_f32_e32 v139, v153, v155
	v_lshlrev_b32_e32 v152, 16, v66
	v_and_b32_e32 v153, 0xffff0000, v66
	v_lshlrev_b32_e32 v154, 16, v162
	v_and_b32_e32 v155, 0xffff0000, v162
	v_sub_f32_e32 v154, v154, v152
	v_sub_f32_e32 v155, v155, v153
	v_fma_f32 v146, v110, v154, v152
	v_fma_f32 v147, v111, v155, v153
	v_lshlrev_b32_e32 v152, 16, v59
	v_and_b32_e32 v153, 0xffff0000, v59
	v_lshlrev_b32_e32 v154, 16, v63
	v_and_b32_e32 v155, 0xffff0000, v63
	v_add_f32_e32 v140, v152, v154
	v_add_f32_e32 v141, v153, v155
	v_lshlrev_b32_e32 v152, 16, v67
	v_and_b32_e32 v153, 0xffff0000, v67
	v_lshlrev_b32_e32 v154, 16, v163
	v_and_b32_e32 v155, 0xffff0000, v163
; DI float sigmoidf_(float x) { return frcp(1.f + __expf(-x)); }
; DI void post1_rows(const Params& p, int l, int nrows, int bid, int nb) {
;     ...
; #pragma unroll
;     for (int hh = 0; hh < 8; ++hh) {
;       const int col = hh * 64 + lane;
;       const float y = yv[hh];
;       const float mean = wave_sum_dpp(y) * (1.f / 64.f);
;       const float d = y - mean;
;       const float var = wave_sum_dpp(d * d) * (1.f / 64.f);
;       float o = d * rsqrtf(var + 64e-5f) * ng[col];
;       o += bonv[hh] * vsv[hh];
;       U[(size_t)row * 512 + col] = f2bf(o);
;     }
; #pragma unroll
;     for (int jj = 0; jj < 2; ++jj) {
;       const int col = 1792 + jj * 64 + lane;
;       const float zg = zshift(Z, row, nrow, col, mu[col]);
;       SG[(size_t)row * 128 + jj * 64 + lane] = f2bf(sigmoidf_(zg));
;     }
	v_sub_f32_e32 v154, v154, v152
	v_sub_f32_e32 v155, v155, v153
	v_fma_f32 v148, v112, v154, v152
	v_fma_f32 v149, v113, v155, v153
	v_add_f32_e32 v156, v134, v135
	v_add_f32_e32 v156, v156, v136
	v_add_f32_e32 v156, v156, v137
	v_add_f32_e32 v156, v156, v138
	v_add_f32_e32 v156, v156, v139
	v_add_f32_e32 v156, v156, v140
	v_add_f32_e32 v156, v156, v141
	v_add_f32_e32 v157, v84, v85
	s_nop 0
	v_add_f32_dpp v156, v156, v156 quad_perm:[1,0,3,2] row_mask:0xf bank_mask:0xf bound_ctrl:1
	s_nop 1
	v_add_f32_dpp v156, v156, v156 quad_perm:[2,3,0,1] row_mask:0xf bank_mask:0xf bound_ctrl:1
	s_nop 1
	v_add_f32_dpp v156, v156, v156 row_half_mirror row_mask:0xf bank_mask:0xf bound_ctrl:1
	v_mul_f32_e32 v156, 0x3c800000, v156
	v_sub_f32_e32 v134, v134, v156
	v_sub_f32_e32 v135, v135, v156
	v_sub_f32_e32 v136, v136, v156
	v_sub_f32_e32 v137, v137, v156
	v_sub_f32_e32 v138, v138, v156
	v_sub_f32_e32 v139, v139, v156
	v_sub_f32_e32 v140, v140, v156
	v_sub_f32_e32 v141, v141, v156
	v_mul_f32_e32 v158, v134, v134
	v_fmac_f32_e32 v158, v135, v135
	v_fmac_f32_e32 v158, v136, v136
	v_fmac_f32_e32 v158, v137, v137
	v_fmac_f32_e32 v158, v138, v138
	v_fmac_f32_e32 v158, v139, v139
	v_fmac_f32_e32 v158, v140, v140
	v_fmac_f32_e32 v158, v141, v141
	s_nop 1
	v_add_f32_dpp v158, v158, v158 quad_perm:[1,0,3,2] row_mask:0xf bank_mask:0xf bound_ctrl:1
	s_nop 1
	v_add_f32_dpp v158, v158, v158 quad_perm:[2,3,0,1] row_mask:0xf bank_mask:0xf bound_ctrl:1
	s_nop 1
	v_add_f32_dpp v158, v158, v158 row_half_mirror row_mask:0xf bank_mask:0xf bound_ctrl:1
	v_mul_f32_e32 v158, 0x3c800000, v158
	v_add_f32_e32 v158, 0x3a27c5ac, v158
	v_rsq_f32_e32 v158, v158
	s_nop 0
	v_mul_f32_e32 v134, v134, v158
	v_mul_f32_e32 v135, v135, v158
	v_mul_f32_e32 v136, v136, v158
	v_mul_f32_e32 v137, v137, v158
	v_mul_f32_e32 v138, v138, v158
	v_mul_f32_e32 v139, v139, v158
	v_mul_f32_e32 v140, v140, v158
	v_mul_f32_e32 v141, v141, v158
	v_mul_f32_e32 v142, v142, v157
	v_mul_f32_e32 v143, v143, v157
	v_mul_f32_e32 v144, v144, v157
	v_mul_f32_e32 v145, v145, v157
	v_mul_f32_e32 v146, v146, v157
	v_mul_f32_e32 v147, v147, v157
	v_mul_f32_e32 v148, v148, v157
	v_mul_f32_e32 v149, v149, v157
	v_fmac_f32_e32 v142, v134, v114
	v_fmac_f32_e32 v143, v135, v115
	v_fmac_f32_e32 v144, v136, v116
	v_fmac_f32_e32 v145, v137, v117
	v_fmac_f32_e32 v146, v138, v118
	v_fmac_f32_e32 v147, v139, v119
	v_fmac_f32_e32 v148, v140, v120
	v_fmac_f32_e32 v149, v141, v121
	v_cvt_pk_bf16_f32 v164, v142, v143
	v_cvt_pk_bf16_f32 v165, v144, v145
	v_cvt_pk_bf16_f32 v166, v146, v147
	v_cvt_pk_bf16_f32 v167, v148, v149
	s_lshl_b32 s41, s75, 10
	s_add_u32 s42, s26, s41
	s_addc_u32 s43, s27, 0
	global_store_dwordx4 v130, v[164:167], s[42:43]
	v_and_b32_e32 v150, s68, v90
	v_and_or_b32 v160, v94, s69, v150
	v_and_b32_e32 v151, s70, v99
	v_and_or_b32 v161, v103, s71, v151
	v_and_b32_e32 v150, s68, v92
	v_and_or_b32 v162, v96, s69, v150
	v_and_b32_e32 v151, s70, v101
	v_and_or_b32 v163, v105, s71, v151
	v_lshlrev_b32_e32 v152, 16, v86
	v_and_b32_e32 v153, 0xffff0000, v86
	v_lshlrev_b32_e32 v154, 16, v160
	v_and_b32_e32 v155, 0xffff0000, v160
	v_sub_f32_e32 v154, v154, v152
	v_sub_f32_e32 v155, v155, v153
	v_fma_f32 v134, v122, v154, v152
	v_fma_f32 v135, v123, v155, v153
	v_lshlrev_b32_e32 v152, 16, v87
	v_and_b32_e32 v153, 0xffff0000, v87
	v_lshlrev_b32_e32 v154, 16, v161
	v_and_b32_e32 v155, 0xffff0000, v161
	v_sub_f32_e32 v154, v154, v152
	v_sub_f32_e32 v155, v155, v153
	v_fma_f32 v136, v124, v154, v152
	v_fma_f32 v137, v125, v155, v153
	v_lshlrev_b32_e32 v152, 16, v88
	v_and_b32_e32 v153, 0xffff0000, v88
	v_lshlrev_b32_e32 v154, 16, v162
	v_and_b32_e32 v155, 0xffff0000, v162
	v_sub_f32_e32 v154, v154, v152
	v_sub_f32_e32 v155, v155, v153
	v_fma_f32 v138, v126, v154, v152
	v_fma_f32 v139, v127, v155, v153
	v_lshlrev_b32_e32 v152, 16, v89
	v_and_b32_e32 v153, 0xffff0000, v89
	v_lshlrev_b32_e32 v154, 16, v163
	v_and_b32_e32 v155, 0xffff0000, v163
	v_sub_f32_e32 v154, v154, v152
	v_sub_f32_e32 v155, v155, v153
	v_fma_f32 v140, v128, v154, v152
	v_fma_f32 v141, v129, v155, v153
	v_mul_f32_e32 v134, 0xbfb8aa3b, v134
	v_mul_f32_e32 v135, 0xbfb8aa3b, v135
	v_mul_f32_e32 v136, 0xbfb8aa3b, v136
	v_mul_f32_e32 v137, 0xbfb8aa3b, v137
	v_mul_f32_e32 v138, 0xbfb8aa3b, v138
	v_mul_f32_e32 v139, 0xbfb8aa3b, v139
	v_mul_f32_e32 v140, 0xbfb8aa3b, v140
	v_mul_f32_e32 v141, 0xbfb8aa3b, v141
	v_exp_f32_e32 v134, v134
	v_exp_f32_e32 v135, v135
	v_exp_f32_e32 v136, v136
	v_exp_f32_e32 v137, v137
	v_exp_f32_e32 v138, v138
	v_exp_f32_e32 v139, v139
	v_exp_f32_e32 v140, v140
	v_exp_f32_e32 v141, v141
	s_nop 0
	v_add_f32_e32 v134, 1.0, v134
	v_add_f32_e32 v135, 1.0, v135
	v_add_f32_e32 v136, 1.0, v136
	v_add_f32_e32 v137, 1.0, v137
	v_add_f32_e32 v138, 1.0, v138
	v_add_f32_e32 v139, 1.0, v139
	v_add_f32_e32 v140, 1.0, v140
	v_add_f32_e32 v141, 1.0, v141
	v_rcp_f32_e32 v134, v134
	v_rcp_f32_e32 v135, v135
	v_rcp_f32_e32 v136, v136
	v_rcp_f32_e32 v137, v137
	v_rcp_f32_e32 v138, v138
	v_rcp_f32_e32 v139, v139
	v_rcp_f32_e32 v140, v140
	v_rcp_f32_e32 v141, v141
	s_nop 0
	v_cvt_pk_bf16_f32 v164, v134, v135
	v_cvt_pk_bf16_f32 v165, v136, v137
	v_cvt_pk_bf16_f32 v166, v138, v139
	v_cvt_pk_bf16_f32 v167, v140, v141
	s_lshl_b32 s41, s75, 8
	s_add_u32 s42, s28, s41
	s_addc_u32 s43, s29, 0
	s_mov_b64 exec, s[72:73]
	global_store_dwordx4 v130, v[164:167], s[42:43]
	s_mov_b64 exec, -1
; DI float bf2f(u16 v) { return __uint_as_float(((unsigned)v) << 16); }
; DI float sigmoidf_(float x) { return frcp(1.f + __expf(-x)); }
; DI void post1_rows(const Params& p, int l, int nrows, int bid, int nb) {
;     ...
;   for (int row = bid * 4 + wid; row < nrows; row += nw) {
;     const int nrow = shift_nbr(row, lane);
;     float yv[8], vsv[8], bonv[8];
; #pragma unroll
;     for (int hh = 0; hh < 8; ++hh) {
;       const int col = hh * 64 + lane;
;       yv[hh] = bf2f(YF[(size_t)row * 512 + col]) + bf2f(YB[(size_t)row * 512 + col]);
;       bonv[hh] = BF[(size_t)row * 8 + hh] + BB[(size_t)row * 8 + hh];
;       vsv[hh] = zshift(Z, row, nrow, 1024 + col, mu[1024 + col]);
;     }
; #pragma unroll
;     for (int hh = 0; hh < 8; ++hh) {
;       const int col = hh * 64 + lane;
;       const float y = yv[hh];
;       const float mean = wave_sum_dpp(y) * (1.f / 64.f);
;       const float d = y - mean;
;       const float var = wave_sum_dpp(d * d) * (1.f / 64.f);
;       float o = d * rsqrtf(var + 64e-5f) * ng[col];
;       o += bonv[hh] * vsv[hh];
;       U[(size_t)row * 512 + col] = f2bf(o);
;     }
; #pragma unroll
;     for (int jj = 0; jj < 2; ++jj) {
;       const int col = 1792 + jj * 64 + lane;
;       const float zg = zshift(Z, row, nrow, col, mu[col]);
;       SG[(size_t)row * 128 + jj * 64 + lane] = f2bf(sigmoidf_(zg));
;     }
;   }
; }
.Lp1_exit:
	s_waitcnt vmcnt(0)
	v_readlane_b32 s0, v255, 0
	v_readlane_b32 s1, v255, 1
	v_readlane_b32 s2, v255, 2
	v_readlane_b32 s3, v255, 3
	v_readlane_b32 s4, v255, 4
	v_readlane_b32 s5, v255, 5
	v_readlane_b32 s6, v255, 6
	v_readlane_b32 s7, v255, 7
	v_readlane_b32 s8, v255, 8
	v_readlane_b32 s9, v255, 9
	v_readlane_b32 s10, v255, 10
	v_readlane_b32 s11, v255, 11
	v_readlane_b32 s12, v255, 12
	v_readlane_b32 s13, v255, 13
	v_readlane_b32 s14, v255, 14
	v_readlane_b32 s15, v255, 15
	v_readlane_b32 s16, v255, 16
	v_readlane_b32 s17, v255, 17
	v_readlane_b32 s18, v255, 18
	v_readlane_b32 s19, v255, 19
	v_readlane_b32 s20, v255, 20
	v_readlane_b32 s21, v255, 21
	v_readlane_b32 s22, v255, 22
	v_readlane_b32 s23, v255, 23
	v_readlane_b32 s24, v255, 24
	v_readlane_b32 s25, v255, 25
	v_readlane_b32 s26, v255, 26
	v_readlane_b32 s27, v255, 27
	v_readlane_b32 s28, v255, 28
	v_readlane_b32 s29, v255, 29
	v_readlane_b32 s30, v255, 30
	v_readlane_b32 s31, v255, 31
	v_readlane_b32 s32, v255, 32
	v_readlane_b32 s33, v255, 33
	v_readlane_b32 s34, v255, 34
	v_readlane_b32 s35, v255, 35
	v_readlane_b32 s36, v255, 36
	v_readlane_b32 s37, v255, 37
	v_readlane_b32 s38, v255, 38
	v_readlane_b32 s39, v255, 39
	v_readlane_b32 s40, v255, 40
	v_readlane_b32 s41, v255, 41
	v_readlane_b32 s42, v255, 42
	v_readlane_b32 s43, v255, 43
	v_readlane_b32 s44, v255, 44
	v_readlane_b32 s45, v255, 45
	v_readlane_b32 s46, v255, 46
	v_readlane_b32 s47, v255, 47
	v_readlane_b32 s48, v255, 48
	v_readlane_b32 s49, v255, 49
	v_readlane_b32 s50, v255, 50
	v_readlane_b32 s51, v255, 51
	v_readlane_b32 s52, v255, 52
	v_readlane_b32 s53, v255, 53
	v_readlane_b32 s54, v255, 54
	v_readlane_b32 s55, v255, 55
	v_readlane_b32 s56, v255, 56
	v_readlane_b32 s57, v255, 57
	v_readlane_b32 s58, v255, 58
	v_readlane_b32 s59, v255, 59
	v_readlane_b32 s60, v255, 60
	v_readlane_b32 s61, v255, 61
	v_readlane_b32 s62, v255, 62
	v_readlane_b32 s63, v255, 63
	v_readlane_b32 s64, v254, 0
	v_readlane_b32 s65, v254, 1
	v_readlane_b32 s66, v254, 2
	v_readlane_b32 s67, v254, 3
	v_readlane_b32 s68, v254, 4
	v_readlane_b32 s69, v254, 5
	v_readlane_b32 s70, v254, 6
	v_readlane_b32 s71, v254, 7
	v_readlane_b32 s72, v254, 8
	v_readlane_b32 s73, v254, 9
	v_readlane_b32 s74, v254, 10
	v_readlane_b32 s75, v254, 11
	v_readlane_b32 s76, v254, 12
	v_readlane_b32 s77, v254, 13

; __global__ void __launch_bounds__(256, 2) mega_kernel(Params p) {
;     ...
;     if (ph + 1 < NPHASE) {
;       if (ph == 0) grid.sync();
;       else xcd_barrier(xb);
;     }
.LBB0_915:
	v_readlane_b32 s4, v243, 7
	s_cmp_lg_u32 s4, -1
	s_mov_b64 s[0:1], -1
	s_cselect_b64 s[22:23], -1, 0
	s_andn2_b64 vcc, exec, s[22:23]
	s_mov_b64 s[22:23], 0
	s_cbranch_vccnz .LBB0_912
